# attention meta tile: the 4 PV MFMAs take inline-zero SrcC, the 16 VALU ops that built a zero accumulator removed
# speedup vs baseline: 1.0062x; 1.0062x over previous
; DI void attn_item(const Params& p, unsigned char* lds, int b, int hd, int qb, float lam) {
;     ...
;     const int qs = qb * 128 + rt * 32 + l31;
;     const size_t grow = (size_t)b * 4096 + qs;
;     bf16x8 qf[4];
; #pragma unroll
;     for (int ks = 0; ks < 4; ++ks) qf[ks] = *(const bf16x8*)(aq + grow * 1024 + hd * 128 + sub * 64 + ks * 16 + 8 * h);
;     f32x16 O[4];
; #pragma unroll
;     for (int d = 0; d < 4; ++d)
; #pragma unroll
;         for (int i = 0; i < 16; ++i) O[d][i] = 0.f;
;     float m = 0.f, l = 0.f;
;     const int T = 2 * qb + 3;
;     u32x4 k0r[2], v0r[2];
;     const int krow_ = tid >> 4, kc_ = tid & 15, vdv_ = tid >> 3, vc_ = tid & 7;
;     const bf16_t* kp = ak + ((size_t)b * 4096 + krow_) * 1024 + hd * 128 + kc_ * 8;
;     const bf16_t* vp_ = avT + ((size_t)(b * 8 + hd) * 128 + vdv_) * 4096 + vc_ * 8;
;     ...
;     {
;         const bf16_t* km_ = akm + (size_t)krow_ * 1024 + hd * 128 + kc_ * 8;
;         k0r[0] = *(const u32x4*)km_; k0r[1] = *(const u32x4*)(km_ + 32 * 1024);
;         const bf16_t* vm_ = avTm + (size_t)(hd * 128 + vdv_) * 64 + vc_ * 8;
;         v0r[0] = *(const u32x4*)vm_; v0r[1] = *(const u32x4*)(vm_ + 64 * 64);
;     }
;     u32x4 k1r[2], v1r[2];
;     A_LOAD_REAL(k1r, v1r);
; #pragma unroll
;     for (int ks = 0; ks < 4; ++ks) asm volatile("" : "+v"(qf[ks]));
;     A_STORE(k0r, v0r, 0);
; DI void phase2(const Params& p, unsigned char* lds) {
;     ...
;         const unsigned x = item >> 16, idx = item & 0xffffu;
;         if (idx < N_GLA) { const unsigned gi = x * N_GLA + idx; gla_item<GLA_DL>(p, lds, gi / (4 * NSL), (gi / NSL) & 3, gi % NSL); }
;         else { const unsigned a = idx - N_GLA, pair = 4 * x + ((a >> 2) & 3); attn_item(p, lds, pair & 3, pair >> 2, 31 - (int)(((a >> 4) << 2) + (a & 3)), lam); }
.Lq_noclaim:
	s_add_i32 s4, s0, -8
	s_lshr_b32 s0, s4, 2
	s_and_b32 s0, s0, 0x3ffffffc
	s_and_b32 s5, s8, 3
	s_or_b32 s0, s0, s5
	v_mov_b32_e32 v132, v186
	s_sub_i32 s0, 31, s0
	s_lshl_b32 s6, s0, 7
	v_lshrrev_b32_e32 v1, 1, v132
	v_and_b32_e32 v146, 31, v132
	v_and_b32_e32 v148, 0x60, v1
	s_bfe_u32 s11, s4, 0x20002
	v_or3_b32 v138, v148, s6, v146
	s_lshl_b32 s54, s11, 12
	v_ashrrev_i32_e32 v139, 31, v138
	v_lshl_add_u64 v[2:3], v[138:139], 0, s[54:55]
	v_ashrrev_i32_e32 v147, 8, v132
	v_lshlrev_b64 v[136:137], 11, v[2:3]
	v_lshl_add_u64 v[2:3], s[68:69], 0, v[136:137]
	s_lshl_b32 s6, s9, 8
	s_mov_b32 s7, s55
	v_lshlrev_b32_e32 v4, 6, v147
	v_lshl_add_u64 v[2:3], v[2:3], 0, s[6:7]
	v_ashrrev_i32_e32 v5, 31, v4
	v_lshl_add_u64 v[2:3], v[4:5], 1, v[2:3]
	v_ashrrev_i32_e32 v4, 4, v132
	v_ashrrev_i32_e32 v5, 31, v4
	v_lshlrev_b64 v[12:13], 11, v[4:5]
	v_bfe_u32 v149, v132, 5, 1
	v_lshlrev_b32_e32 v1, 4, v132
	v_lshl_add_u64 v[12:13], s[64:65], 0, v[12:13]
	v_lshlrev_b32_e32 v98, 4, v149
	v_and_b32_e32 v140, 0xf0, v1
	v_mov_b32_e32 v141, v99
	v_lshl_add_u64 v[12:13], v[12:13], 0, s[6:7]
	v_lshl_add_u64 v[2:3], v[2:3], 0, v[98:99]
	v_lshl_add_u64 v[12:13], v[12:13], 0, v[140:141]
	global_load_dwordx4 v[100:103], v[2:3], off
	global_load_dwordx4 v[104:107], v[2:3], off offset:32
	global_load_dwordx4 v[108:111], v[2:3], off offset:64
	global_load_dwordx4 v[112:115], v[2:3], off offset:96
	global_load_dwordx4 v[116:119], v[12:13], off
	v_add_co_u32_e32 v2, vcc, s43, v12
	s_lshl_b32 s10, s9, 7
	v_ashrrev_i32_e32 v6, 3, v132
	v_addc_co_u32_e32 v3, vcc, 0, v13, vcc
	global_load_dwordx4 v[120:123], v[2:3], off
	v_add_u32_e32 v2, s10, v6
	v_ashrrev_i32_e32 v3, 31, v2
	v_lshlrev_b64 v[2:3], 7, v[2:3]
	v_and_b32_e32 v10, 0x70, v1
	v_mov_b32_e32 v11, v99
	v_lshl_add_u64 v[2:3], s[62:63], 0, v[2:3]
	v_lshl_add_u64 v[2:3], v[2:3], 0, v[10:11]
	global_load_dwordx4 v[124:127], v[2:3], off
	v_lshl_add_u64 v[8:9], v[4:5], 0, s[54:55]
	v_lshlrev_b64 v[8:9], 11, v[8:9]
	v_add_co_u32_e32 v2, vcc, s56, v2
	v_lshl_add_u64 v[8:9], s[44:45], 0, v[8:9]
	s_lshl_b32 s11, s11, 10
	v_addc_co_u32_e32 v3, vcc, 0, v3, vcc
	v_lshl_add_u64 v[8:9], v[8:9], 0, s[6:7]
	s_add_i32 s54, s11, s10
	v_ashrrev_i32_e32 v7, 31, v6
	global_load_dwordx4 v[128:131], v[2:3], off
	v_lshl_add_u64 v[82:83], v[8:9], 0, v[140:141]
	v_lshl_add_u64 v[8:9], v[6:7], 0, s[54:55]
	v_lshlrev_b64 v[8:9], 13, v[8:9]
	v_lshl_add_u64 v[8:9], s[60:61], 0, v[8:9]
	v_add_co_u32_e32 v2, vcc, s43, v82
	v_lshl_add_u64 v[84:85], v[8:9], 0, v[10:11]
	s_nop 0
	v_addc_co_u32_e32 v3, vcc, 0, v83, vcc
	v_add_co_u32_e32 v8, vcc, s74, v84
	global_load_dwordx4 v[74:77], v[82:83], off
	global_load_dwordx4 v[70:73], v[84:85], off
	v_addc_co_u32_e32 v9, vcc, 0, v85, vcc
	global_load_dwordx4 v[78:81], v[2:3], off
	global_load_dwordx4 v[66:69], v[8:9], off
	v_lshlrev_b32_e32 v2, 3, v132
	v_mul_lo_u32 v139, v4, s75
	v_add_u32_e32 v4, 0x200, v132
	v_and_b32_e32 v150, 0x60, v1
	v_and_b32_e32 v151, 8, v2
	v_lshrrev_b32_e32 v5, 4, v4
	v_add3_u32 v1, 0, v150, v151
	v_mul_lo_u32 v152, v6, s52
	v_add_u32_e32 v3, 0, v140
	v_mul_lo_u32 v141, v5, s75
	v_add_u32_e32 v97, v1, v152
	v_add_u32_e32 v87, v3, v139
	v_add_u32_e32 v96, v3, v141
	v_add_u32_e32 v2, 0x4000, v97
	s_waitcnt vmcnt(11)
	s_waitcnt vmcnt(10)
	s_waitcnt vmcnt(9)
	s_waitcnt vmcnt(8)
	s_waitcnt vmcnt(7)
	ds_write_b128 v87, v[116:119]
	v_mad_u32_u24 v42, v146, s75, 0
	v_lshl_or_b32 v154, v147, 7, v98
	s_waitcnt vmcnt(6)
	ds_write_b128 v96, v[120:123]
	s_waitcnt vmcnt(5)
	ds_write2_b64 v2, v[124:125], v[126:127] offset0:128 offset1:130
	v_lshrrev_b32_e32 v2, 3, v4
	v_mul_lo_u32 v153, v2, s52
	v_add_u32_e32 v155, v1, v153
	v_add_u32_e32 v1, 0x4000, v155
	s_waitcnt vmcnt(4)
	ds_write2_b64 v1, v[128:129], v[130:131] offset0:128 offset1:130
	v_add_u32_e32 v1, v42, v154
	s_waitcnt lgkmcnt(0)
	s_barrier
; DI void attn_s(const unsigned char* sK, int tt, int qb, int qs, int sub, int l31, int h,
;                const bf16x8 (&qf)[4], f32x16 (&O)[4], float& m, float& l, bf16x8 (&pb)[4]) {
;     ...
;         for (int i = 0; i < 16; ++i) st[k2][i] = -m;
;     {
;         const unsigned char* kb = sK + l31 * A_KROWB + (sub * 64 + 8 * h) * 2;
;         bf16x8 ka[4], kc[4];
; #pragma unroll
;         for (int i = 0; i < 4; ++i) ka[i] = *(const bf16x8*)(kb + (i & 1) * 32 * A_KROWB + (i >> 1) * 32);
;         __builtin_amdgcn_sched_barrier(0);
; #pragma unroll
;         for (int i = 0; i < 4; ++i) kc[i] = *(const bf16x8*)(kb + (i & 1) * 32 * A_KROWB + (2 + (i >> 1)) * 32);
;         __builtin_amdgcn_sched_barrier(0);
; #pragma unroll
;         for (int i = 0; i < 4; ++i) st[i & 1] = MFMA32(ka[i], qf[i >> 1], st[i & 1]);
;         __builtin_amdgcn_sched_barrier(0);
; #pragma unroll
;         for (int i = 0; i < 4; ++i) st[i & 1] = MFMA32(kc[i], qf[2 + (i >> 1)], st[i & 1]);
;     }
;     if (tt == 0) {
; #pragma unroll
;         for (int i = 0; i < 16; ++i) { st[0][i] = -INFINITY; if (i < 8) st[1][i] = -INFINITY; }
;     } else if (tt >= 2 * qb + 1) {
;         const int kbase = (tt - 1) * 64 + 4 * h;
; #pragma unroll
;         for (int k2 = 0; k2 < 2; ++k2)
; #pragma unroll
;             for (int i = 0; i < 16; ++i) {
;                 const int key = kbase + k2 * 32 + (i & 3) + 8 * (i >> 2);
;                 if (key > qs) st[k2][i] = -INFINITY;
;             }
;     }
;     float mx;
;     {
;         float t[11];
; #pragma unroll
;         for (int i = 0; i < 5; ++i) t[i] = max3f(st[0][3 * i], st[0][3 * i + 1], st[0][3 * i + 2]);
; #pragma unroll
;         for (int i = 0; i < 5; ++i) t[5 + i] = max3f(st[1][3 * i], st[1][3 * i + 1], st[1][3 * i + 2]);
;         t[10] = fmaxf(st[0][15], st[1][15]);
;         const float u0 = max3f(t[0], t[1], t[2]), u1 = max3f(t[3], t[4], t[5]), u2 = max3f(t[6], t[7], t[8]);
;         mx = max3f(max3f(u0, u1, u2), t[9], t[10]);
;     }
;     mx = xor32_max(mx);
;     if (tt == 0 || __builtin_amdgcn_ballot_w64(mx > 8.0f) != 0ull) {
;         const float delta = tt == 0 ? mx : fmaxf(mx, 0.f);
;         const float alpha = __builtin_amdgcn_exp2f(-delta);
;         m += delta;
;         l *= alpha;
; #pragma unroll
;         for (int d = 0; d < 4; ++d) O[d] = O[d] * alpha;
; #pragma unroll
	ds_read_b128 v[26:29], v1 offset:8704
	ds_read_b128 v[30:33], v1 offset:8736
	ds_read_b128 v[34:37], v1 offset:8768
	ds_read_b128 v[38:41], v1 offset:8800
	v_mov_b32_e32 v10, v0
	v_mov_b32_e32 v11, v0
	v_mov_b32_e32 v12, v0
	v_mov_b32_e32 v13, v0
	v_mov_b32_e32 v14, v0
	v_mov_b32_e32 v15, v0
	v_mov_b32_e32 v1, v0
	v_mov_b32_e32 v2, v0
	v_mov_b32_e32 v3, v0
	v_mov_b32_e32 v4, v0
	v_mov_b32_e32 v5, v0
	v_mov_b32_e32 v6, v0
	v_mov_b32_e32 v7, v0
	v_mov_b32_e32 v8, v0
	v_mov_b32_e32 v9, v0
	v_mov_b64_e32 v[24:25], v[14:15]
	v_mov_b64_e32 v[22:23], v[12:13]
	v_mov_b64_e32 v[20:21], v[10:11]
	v_mov_b64_e32 v[18:19], v[8:9]
	v_mov_b64_e32 v[16:17], v[6:7]
	v_mov_b64_e32 v[14:15], v[4:5]
	v_mov_b64_e32 v[12:13], v[2:3]
	v_mov_b64_e32 v[10:11], v[0:1]
	s_waitcnt lgkmcnt(3)
	s_nop 0
	v_mfma_f32_32x32x16_bf16 v[10:25], v[26:29], v[100:103], v[10:25]
	s_waitcnt lgkmcnt(2)
	v_mfma_f32_32x32x16_bf16 v[10:25], v[30:33], v[104:107], v[10:25]
	s_waitcnt lgkmcnt(1)
	v_mfma_f32_32x32x16_bf16 v[10:25], v[34:37], v[108:111], v[10:25]
	v_max3_f32 v1, v188, v188, v188
	s_nop 0
	v_max3_f32 v2, v1, v1, v1
	s_waitcnt lgkmcnt(0)
	v_mfma_f32_32x32x16_bf16 v[10:25], v[38:41], v[112:115], v[10:25]
	v_max3_f32 v3, v188, v188, v18
	v_max3_f32 v4, v19, v20, v21
	v_max3_f32 v5, v22, v23, v24
	s_nop 0
	v_max3_f32 v1, v1, v3, v4
	s_nop 10
	v_max_f32_e32 v6, v25, v25
	v_max3_f32 v1, v2, v2, v1
	v_max_f32_e32 v6, 0xff800000, v6
	v_max3_f32 v1, v1, v5, v6
	s_nop 0
	v_mov_b32_e32 v2, v1
	s_nop 1
	v_permlane32_swap_b32_e32 v1, v2
	v_max_f32_e32 v2, v2, v2
	v_max_f32_e32 v1, v1, v1
	v_max_f32_e32 v86, v1, v2
	v_sub_f32_e32 v1, 0xff800000, v86
	v_sub_f32_e32 v19, v19, v86
	v_sub_f32_e32 v26, v18, v86
	v_sub_f32_e32 v21, v21, v86
	v_sub_f32_e32 v20, v20, v86
	v_exp_f32_e32 v18, v1
	v_exp_f32_e32 v26, v26
	v_exp_f32_e32 v27, v19
	v_sub_f32_e32 v23, v23, v86
	v_sub_f32_e32 v22, v22, v86
	v_exp_f32_e32 v28, v20
	v_exp_f32_e32 v29, v21
	v_sub_f32_e32 v25, v25, v86
	v_sub_f32_e32 v24, v24, v86
	v_exp_f32_e32 v30, v22
	v_exp_f32_e32 v31, v23
	v_exp_f32_e32 v32, v24
	v_exp_f32_e32 v33, v25
	v_pk_add_f32 v[34:35], v[18:19], v[26:27] op_sel_hi:[0,1]
	v_add_f32_e32 v36, v18, v18
	v_pk_add_f32 v[24:25], v[18:19], v[28:29] op_sel_hi:[0,1]
	v_mov_b32_e32 v37, v34
	v_mov_b32_e32 v34, v36
	v_pk_add_f32 v[22:23], v[18:19], v[30:31] op_sel_hi:[0,1]
	v_pk_add_f32 v[34:35], v[36:37], v[34:35]
	v_mov_b32_e32 v37, v24
	v_mov_b32_e32 v24, v36
	v_pk_add_f32 v[20:21], v[18:19], v[32:33] op_sel_hi:[0,1]
	v_pk_add_f32 v[24:25], v[36:37], v[24:25]
	v_mov_b32_e32 v37, v22
	v_mov_b32_e32 v22, v36
	v_pk_add_f32 v[22:23], v[36:37], v[22:23]
	v_mov_b32_e32 v37, v20
	v_mov_b32_e32 v20, v36
	v_pk_add_f32 v[20:21], v[36:37], v[20:21]
	v_cvt_pk_bf16_f32 v88, v18, v18
	v_lshlrev_b32_e32 v18, 7, v146
	v_pk_add_f32 v[24:25], v[34:35], v[24:25]
	v_pk_add_f32 v[20:21], v[22:23], v[20:21]
	v_sub_u32_e32 v18, v42, v18
	v_pk_add_f32 v[20:21], v[24:25], v[20:21]
	v_add_u32_e32 v185, v18, v98
	v_add_f32_e32 v1, v20, v21
	ds_read_b128 v[160:163], v185 offset:17504
	ds_read_b128 v[164:167], v185 offset:22112
	ds_read_b128 v[168:171], v185 offset:26720
	ds_read_b128 v[172:175], v185 offset:31328
	v_exp_f32_e64 v184, -v86
	v_mov_b32_e32 v89, v88
	v_mov_b32_e32 v90, v88
	v_mov_b32_e32 v91, v88
	v_cvt_pk_bf16_f32 v156, v26, v27
	v_cvt_pk_bf16_f32 v157, v28, v29
	v_cvt_pk_bf16_f32 v158, v30, v31
	v_cvt_pk_bf16_f32 v159, v32, v33
	s_waitcnt lgkmcnt(3)
	v_mfma_f32_32x32x16_bf16 v[50:65], v[160:163], v[156:159], 0
	s_waitcnt vmcnt(3)
	ds_write_b128 v87, v[74:77] offset:35840
	s_waitcnt vmcnt(1)
	ds_write_b128 v96, v[78:81] offset:35840
	v_add_u32_e32 v74, 0xd000, v97
	ds_write2_b64 v74, v[70:71], v[72:73] offset1:2
	v_add_u32_e32 v70, 0xd000, v155
	v_fmac_f32_e32 v1, 0, v184
	s_cmpk_gt_u32 s4, 0x7f
	s_waitcnt vmcnt(0)
	ds_write2_b64 v70, v[66:67], v[68:69] offset1:2
	v_readfirstlane_b32 s99, v238
	s_nop 3
	v_writelane_b32 v236, s99, 63
	s_waitcnt lgkmcnt(6)
	v_mfma_f32_32x32x16_bf16 v[34:49], v[164:167], v[156:159], 0
	s_waitcnt lgkmcnt(0)
	s_barrier
	v_mfma_f32_32x32x16_bf16 v[18:33], v[168:171], v[156:159], 0
	v_mfma_f32_32x32x16_bf16 v[2:17], v[172:175], v[156:159], 0
	s_cbranch_scc1 .LBB0_1824
	s_lshr_b32 s4, s4, 1
	s_lshl_b32 s5, s5, 1
	s_and_b32 s4, s4, 0x7ffffff8
	s_lshl_b32 s0, s0, 1
	s_or_b32 s4, s5, s4
	v_mul_u32_u24_e32 v155, 0x110, v146
	v_mul_u32_u24_e32 v156, 0x90, v146
	s_mov_b32 s13, 1
	s_add_i32 s6, s0, 3
	v_lshl_add_u64 v[142:143], v[84:85], 0, s[88:89]
	v_lshl_add_u64 v[142:143], v[142:143], 0, s[88:89]
	v_add_f32_e32 v157, 0, v86
	v_lshl_add_u64 v[144:145], v[82:83], 0, s[90:91]
	v_lshl_add_u64 v[144:145], v[144:145], 0, s[90:91]
	s_mov_b32 s7, 2
	v_lshl_or_b32 v158, v149, 2, 59
	s_sub_i32 s11, 0, s4
	s_movk_i32 s12, 0xffc0
	v_xor_b32_e32 v240, 0x80000000, v157
	v_mov_b32_e32 v241, v240
	v_mov_b32_e32 v242, v240
	v_mov_b32_e32 v243, v240
	v_mov_b32_e32 v244, v240
	v_mov_b32_e32 v245, v240
	v_mov_b32_e32 v246, v240
	v_mov_b32_e32 v247, v240
	v_mov_b32_e32 v248, v240
	v_mov_b32_e32 v249, v240
	v_mov_b32_e32 v250, v240
	v_mov_b32_e32 v251, v240
	v_mov_b32_e32 v252, v240
	v_mov_b32_e32 v253, v240
	v_mov_b32_e32 v254, v240
	v_mov_b32_e32 v255, v240
	v_readfirstlane_b32 s99, v147
	s_cmp_eq_u32 s99, 1
	s_cbranch_scc0 .Lpipe_nooffs
	s_barrier
